# slc loop: wave-uniform bookkeeping (remaining-tile mask, tile index) moved from VGPRs to SGPRs
# baseline (speedup 1.0000x reference)
; DI float bf2f(bf16 b) { return __uint_as_float(((unsigned)b) << 16); }
; DI void nsa_unit(const Ctx& c0, int b, int g, int i, LAS unsigned char* lds) {
;     ...
;     bf16x8 qr[4];
;     { const float* ct = (const float*)(c.ws + O_TAB) + (size_t)t * 32; const float* stb = ct + 4096 * 32;
; #pragma unroll
;       for (int s = 0; s < 2; ++s) {
;           const f32x4 c0 = *(const f32x4*)(ct + 16 * s + 8 * hi), c1 = *(const f32x4*)(ct + 16 * s + 8 * hi + 4);
;           const f32x4 s0 = *(const f32x4*)(stb + 16 * s + 8 * hi), s1 = *(const f32x4*)(stb + 16 * s + 8 * hi + 4);
;           float lo_[8], hi_[8], ol[8], oh[8];
; #pragma unroll
;           for (int j = 0; j < 8; ++j) { lo_[j] = bf2f((bf16)qn[s][j]); hi_[j] = bf2f((bf16)qn[s + 2][j]); }
; #pragma unroll
;           for (int j = 0; j < 8; ++j) { const float cc = j < 4 ? c0[j & 3] : c1[j & 3], ss = j < 4 ? s0[j & 3] : s1[j & 3];
;               ol[j] = lo_[j] * cc - hi_[j] * ss; oh[j] = hi_[j] * cc + lo_[j] * ss; }
;           qr[s] = pack8(ol[0], ol[1], ol[2], ol[3], ol[4], ol[5], ol[6], ol[7]); qr[s + 2] = pack8(oh[0], oh[1], oh[2], oh[3], oh[4], oh[5], oh[6], oh[7]); } }
;     ...
;     {
;         const bf16* Kg = (const bf16*)(c.ws + O_KS) + ((size_t)g * T + (size_t)b * SEQ) * 64;
;         const bf16* Vg = (const bf16*)(c.ws + O_VS) + ((size_t)g * T + (size_t)b * SEQ) * 64;
;         ASt st; st.m = NEGB; st.l = 0.f; st.o0 = f32x16{}; st.o1 = f32x16{};
;         unsigned long long rem = um;
;         int n = __builtin_ctzll(rem); rem &= rem - 1ull;
;         TileRegs tr = tile_fetch(Kg, Vg, 64 * n, tid);
;         int k = 0;
.LBB0_565:
	v_lshlrev_b64 v[4:5], 7, v[2:3]
	v_lshl_add_u64 v[4:5], s[0:1], 0, v[4:5]
	v_lshlrev_b32_e32 v2, 2, v124
	v_lshl_add_u64 v[16:17], v[4:5], 0, v[2:3]
	s_mov_b64 s[12:13], 0x2200000
	v_add_co_u32_e32 v4, vcc, 0x2200000, v16
	v_lshl_add_u64 v[24:25], v[16:17], 0, s[12:13]
	s_mov_b64 s[12:13], 0x2280000
	v_addc_co_u32_e32 v5, vcc, 0, v17, vcc
	v_lshl_add_u64 v[14:15], v[16:17], 0, s[12:13]
	v_add_co_u32_e32 v16, vcc, 0x2280000, v16
	global_load_dwordx4 v[4:7], v[4:5], off
	s_nop 0
	global_load_dwordx4 v[8:11], v[24:25], off offset:16
	v_addc_co_u32_e32 v17, vcc, 0, v17, vcc
	global_load_dwordx4 v[16:19], v[16:17], off
	s_nop 0
	global_load_dwordx4 v[20:23], v[14:15], off offset:16
	v_and_b32_e32 v29, 0xffff0000, v108
	v_lshlrev_b32_e32 v28, 16, v108
	v_and_b32_e32 v27, 0xffff0000, v112
	v_lshlrev_b32_e32 v26, 16, v112
	v_ffbl_b32_e32 v2, v13
	s_add_u32 s12, s0, s94
	v_add_u32_e32 v2, 32, v2
	s_addc_u32 s13, s1, s95
	s_add_u32 s88, s12, 0x8400000
	s_addc_u32 s89, s13, 0
	s_add_u32 s90, s12, 0x9400000
	s_addc_u32 s91, s13, 0
	s_mov_b32 s3, 0
	s_mov_b64 s[12:13], 0
	s_waitcnt vmcnt(0) lgkmcnt(0)
	v_pk_mul_f32 v[30:31], v[16:17], v[28:29]
	s_nop 0
	v_pk_fma_f32 v[30:31], v[4:5], v[26:27], v[30:31] neg_lo:[0,0,1] neg_hi:[0,0,1]
	v_pk_mul_f32 v[16:17], v[16:17], v[26:27]
	v_and_b32_e32 v27, 0xffff0000, v109
	v_lshlrev_b32_e32 v26, 16, v109
	v_pk_fma_f32 v[4:5], v[4:5], v[28:29], v[16:17]
	v_and_b32_e32 v17, 0xffff0000, v113
	v_lshlrev_b32_e32 v16, 16, v113
	v_pk_mul_f32 v[28:29], v[18:19], v[26:27]
	v_cvt_pk_bf16_f32 v86, v4, v5
	v_pk_fma_f32 v[28:29], v[6:7], v[16:17], v[28:29] neg_lo:[0,0,1] neg_hi:[0,0,1]
	v_pk_mul_f32 v[16:17], v[18:19], v[16:17]
	v_and_b32_e32 v19, 0xffff0000, v110
	v_lshlrev_b32_e32 v18, 16, v110
	v_pk_fma_f32 v[6:7], v[6:7], v[26:27], v[16:17]
	v_and_b32_e32 v17, 0xffff0000, v114
	v_lshlrev_b32_e32 v16, 16, v114
	v_pk_mul_f32 v[26:27], v[20:21], v[18:19]
	v_cvt_pk_bf16_f32 v87, v6, v7
	v_pk_fma_f32 v[26:27], v[8:9], v[16:17], v[26:27] neg_lo:[0,0,1] neg_hi:[0,0,1]
	v_pk_mul_f32 v[16:17], v[20:21], v[16:17]
	v_cvt_pk_bf16_f32 v84, v26, v27
	v_pk_fma_f32 v[8:9], v[8:9], v[18:19], v[16:17]
	v_and_b32_e32 v19, 0xffff0000, v111
	v_lshlrev_b32_e32 v18, 16, v111
	v_and_b32_e32 v17, 0xffff0000, v115
	v_lshlrev_b32_e32 v16, 16, v115
	v_pk_mul_f32 v[20:21], v[22:23], v[18:19]
	v_cvt_pk_bf16_f32 v88, v8, v9
	v_pk_fma_f32 v[20:21], v[10:11], v[16:17], v[20:21] neg_lo:[0,0,1] neg_hi:[0,0,1]
	v_pk_mul_f32 v[16:17], v[22:23], v[16:17]
	v_cvt_pk_bf16_f32 v85, v20, v21
	v_pk_fma_f32 v[10:11], v[10:11], v[18:19], v[16:17]
	v_cvt_pk_bf16_f32 v82, v30, v31
	v_cvt_pk_bf16_f32 v89, v10, v11
	global_load_dwordx4 v[8:11], v[24:25], off offset:64
	global_load_dwordx4 v[4:7], v[24:25], off offset:80
	global_load_dwordx4 v[16:19], v[14:15], off offset:64
	global_load_dwordx4 v[20:23], v[14:15], off offset:80
	v_and_b32_e32 v25, 0xffff0000, v104
	v_lshlrev_b32_e32 v24, 16, v104
	v_and_b32_e32 v15, 0xffff0000, v100
	v_lshlrev_b32_e32 v14, 16, v100
	v_cvt_pk_bf16_f32 v83, v28, v29
	s_waitcnt vmcnt(0) lgkmcnt(0)
	v_pk_mul_f32 v[26:27], v[16:17], v[24:25]
	s_nop 0
	v_pk_fma_f32 v[26:27], v[8:9], v[14:15], v[26:27] neg_lo:[0,0,1] neg_hi:[0,0,1]
	v_pk_mul_f32 v[14:15], v[16:17], v[14:15]
	v_and_b32_e32 v17, 0xffff0000, v105
	v_lshlrev_b32_e32 v16, 16, v105
	v_pk_fma_f32 v[8:9], v[8:9], v[24:25], v[14:15]
	v_and_b32_e32 v15, 0xffff0000, v101
	v_lshlrev_b32_e32 v14, 16, v101
	v_pk_mul_f32 v[24:25], v[18:19], v[16:17]
	v_cvt_pk_bf16_f32 v90, v26, v27
	v_pk_fma_f32 v[24:25], v[10:11], v[14:15], v[24:25] neg_lo:[0,0,1] neg_hi:[0,0,1]
	v_pk_mul_f32 v[14:15], v[18:19], v[14:15]
	v_cvt_pk_bf16_f32 v91, v24, v25
	v_pk_fma_f32 v[10:11], v[10:11], v[16:17], v[14:15]
	v_and_b32_e32 v17, 0xffff0000, v106
	v_lshlrev_b32_e32 v16, 16, v106
	v_and_b32_e32 v15, 0xffff0000, v102
	v_lshlrev_b32_e32 v14, 16, v102
	v_pk_mul_f32 v[18:19], v[20:21], v[16:17]
	v_cvt_pk_bf16_f32 v94, v8, v9
	v_pk_fma_f32 v[18:19], v[4:5], v[14:15], v[18:19] neg_lo:[0,0,1] neg_hi:[0,0,1]
	v_pk_mul_f32 v[14:15], v[20:21], v[14:15]
	v_cvt_pk_bf16_f32 v92, v18, v19
	v_pk_fma_f32 v[4:5], v[4:5], v[16:17], v[14:15]
	v_and_b32_e32 v17, 0xffff0000, v107
	v_cvt_pk_bf16_f32 v96, v4, v5
	v_ffbl_b32_e32 v4, v12
	v_min_u32_e32 v52, v4, v2
	v_lshl_add_u64 v[4:5], v[12:13], 0, -1
	v_lshlrev_b32_e32 v16, 16, v107
	v_and_b32_e32 v50, v4, v12
	v_lshl_add_u32 v4, v52, 6, v140
	v_and_b32_e32 v15, 0xffff0000, v103
	v_lshlrev_b32_e32 v14, 16, v103
	v_pk_mul_f32 v[20:21], v[22:23], v[16:17]
	v_and_b32_e32 v51, v5, v13
	v_ashrrev_i32_e32 v5, 31, v4
	v_pk_fma_f32 v[20:21], v[6:7], v[14:15], v[20:21] neg_lo:[0,0,1] neg_hi:[0,0,1]
	v_pk_mul_f32 v[14:15], v[22:23], v[14:15]
	v_lshlrev_b64 v[4:5], 7, v[4:5]
	v_pk_fma_f32 v[6:7], v[6:7], v[16:17], v[14:15]
	v_lshl_or_b32 v4, v138, 1, v4
	v_cvt_pk_bf16_f32 v97, v6, v7
	v_lshl_add_u64 v[6:7], s[88:89], 0, v[4:5]
	v_lshl_add_u64 v[4:5], s[90:91], 0, v[4:5]
	global_load_dwordx4 v[98:101], v[6:7], off
	global_load_dwordx4 v[102:105], v[4:5], off
	v_mov_b32_e32 v16, v3
	v_mov_b32_e32 v17, v3
	v_cvt_pk_bf16_f32 v93, v20, v21
	v_cvt_pk_bf16_f32 v95, v10, v11
	v_mov_b32_e32 v2, v3
	v_mov_b32_e32 v4, v3
	v_mov_b32_e32 v5, v3
	v_mov_b32_e32 v6, v3
	v_mov_b32_e32 v7, v3
	v_mov_b32_e32 v8, v3
	v_mov_b32_e32 v9, v3
	v_mov_b32_e32 v10, v3
	v_mov_b32_e32 v11, v3
	v_mov_b32_e32 v12, v3
	v_mov_b32_e32 v13, v3
	v_mov_b32_e32 v14, v3
	v_mov_b32_e32 v15, v3
	v_mov_b64_e32 v[32:33], v[16:17]
	v_mov_b64_e32 v[48:49], v[16:17]
	v_mov_b32_e32 v107, 0xf149f2ca
	v_mov_b32_e32 v106, 0
	v_mov_b64_e32 v[30:31], v[14:15]
	v_mov_b64_e32 v[28:29], v[12:13]
	v_mov_b64_e32 v[26:27], v[10:11]
	v_mov_b64_e32 v[24:25], v[8:9]
	v_mov_b64_e32 v[22:23], v[6:7]
	v_mov_b64_e32 v[20:21], v[4:5]
	v_mov_b64_e32 v[18:19], v[2:3]
	v_mov_b64_e32 v[46:47], v[14:15]
	v_mov_b64_e32 v[44:45], v[12:13]
	v_mov_b64_e32 v[42:43], v[10:11]
	v_mov_b64_e32 v[40:41], v[8:9]
	v_mov_b64_e32 v[38:39], v[6:7]
	v_mov_b64_e32 v[36:37], v[4:5]
	v_mov_b64_e32 v[34:35], v[2:3]
	v_readfirstlane_b32 s98, v50
	v_readfirstlane_b32 s99, v51
	v_readfirstlane_b32 s100, v52
	s_branch .LBB0_568

; #define LAS __attribute__((address_space(3)))
; #define LDS_WAIT() asm volatile("s_waitcnt lgkmcnt(0)" ::: "memory")
; #define MFMA32(a, b, c) __builtin_amdgcn_mfma_f32_32x32x16_bf16((a), (b), (c), 0, 0, 0)
; template <bool CMP> DI void tile_compute(LAS unsigned char* lds, int buf, const bf16x8 (&q)[4], int lo, int hv, ASt& st, f32x16& imp0, f32x16& imp1, int jt, LAS float* wsf, int lane) {
;     ...
;     const float alpha = __builtin_amdgcn_exp2f(st.m - mnew);
;     st.m = mnew;
;     float sum = 0.f;
;     const float msub = (!anyPart && dead) ? 1e30f : mnew;
; #pragma unroll
;     for (int rg = 0; rg < 16; ++rg) { p0[rg] = __builtin_amdgcn_exp2f(p0[rg] - msub); p1[rg] = __builtin_amdgcn_exp2f(p1[rg] - msub); sum += p0[rg] + p1[rg]; }
;     st.l = st.l * alpha + sum;
;     if (__builtin_amdgcn_ballot_w64(alpha != 1.f) != 0ull) {
;         if (hi == 0) wsf[r] = alpha;
;         LDS_WAIT();
; #pragma unroll
;         for (int g4 = 0; g4 < 4; ++g4) { const f32x4 f = *(const LAS f32x4*)(wsf + 8 * g4 + 4 * hi);
; #pragma unroll
;             for (int k = 0; k < 4; ++k) { st.o0[4 * g4 + k] *= f[k]; st.o1[4 * g4 + k] *= f[k]; if (CMP) { imp0[4 * g4 + k] *= f[k]; imp1[4 * g4 + k] *= f[k]; } } }
;         LDS_WAIT();
;     }
;     bf16x8 pa[4];
;     pa[0] = pack8(p0[0], p0[1], p0[2], p0[3], p0[4], p0[5], p0[6], p0[7]); pa[1] = pack8(p0[8], p0[9], p0[10], p0[11], p0[12], p0[13], p0[14], p0[15]);
;     pa[2] = pack8(p1[0], p1[1], p1[2], p1[3], p1[4], p1[5], p1[6], p1[7]); pa[3] = pack8(p1[8], p1[9], p1[10], p1[11], p1[12], p1[13], p1[14], p1[15]);
;     const LAS unsigned char* vb = lds + A_VT + buf * 8192 + (4 * hi + ((lane & 15) >> 2)) * 64 + ((lane >> 4) & 1) * 32 + (lane & 3) * 8;
; #pragma unroll
;     for (int s = 0; s < 4; ++s) {
;         const bf16x8 v0 = cat8(vtr(vb + s * 1024), vtr(vb + s * 1024 + 512));
;         const bf16x8 v1 = cat8(vtr(vb + 4096 + s * 1024), vtr(vb + 4096 + s * 1024 + 512));
;         st.o0 = MFMA32(pa[s], v0, st.o0); st.o1 = MFMA32(pa[s], v1, st.o1);
;     }
; DI void nsa_unit(const Ctx& c0, int b, int g, int i, LAS unsigned char* lds) {
;     ...
;         for (;;) {
;             tile_stage(tr, lds, k & 1, tid);
;             __syncthreads();
;             const bool more = rem != 0ull; int nn = 0;
;             if (more) { nn = __builtin_ctzll(rem); rem &= rem - 1ull; tr = tile_fetch(Kg, Vg, 64 * nn, tid); }
.LBB0_567:
	s_and_b64 s[14:15], exec, s[78:79]
	s_or_b64 s[12:13], s[14:15], s[12:13]
	s_addk_i32 s3, 0x2000
	v_mul_f32_e32 v11, v106, v4
	v_add3_u32 v16, s84, v208, v209
	v_add3_u32 v16, v16, v197, v198
	ds_read_b64_tr_b16 v[108:109], v16 offset:16384
	ds_read_b64_tr_b16 v[110:111], v16 offset:16896
	ds_read_b64_tr_b16 v[112:113], v16 offset:20480
	ds_read_b64_tr_b16 v[114:115], v16 offset:20992
	ds_read_b64_tr_b16 v[120:121], v16 offset:17408
	ds_read_b64_tr_b16 v[122:123], v16 offset:17920
	v_cndmask_b32_e64 v12, v2, v223, s[80:81]
	v_mov_b32_e32 v13, v12
	v_pk_add_f32 v[66:67], v[66:67], v[12:13] neg_lo:[0,1] neg_hi:[0,1]
	v_pk_add_f32 v[68:69], v[68:69], v[12:13] neg_lo:[0,1] neg_hi:[0,1]
	v_pk_add_f32 v[70:71], v[70:71], v[12:13] neg_lo:[0,1] neg_hi:[0,1]
	v_pk_add_f32 v[72:73], v[72:73], v[12:13] neg_lo:[0,1] neg_hi:[0,1]
	v_pk_add_f32 v[74:75], v[74:75], v[12:13] neg_lo:[0,1] neg_hi:[0,1]
	v_pk_add_f32 v[76:77], v[76:77], v[12:13] neg_lo:[0,1] neg_hi:[0,1]
	v_pk_add_f32 v[78:79], v[78:79], v[12:13] neg_lo:[0,1] neg_hi:[0,1]
	v_pk_add_f32 v[80:81], v[80:81], v[12:13] neg_lo:[0,1] neg_hi:[0,1]
	v_exp_f32_e32 v66, v66
	v_exp_f32_e32 v67, v67
	v_exp_f32_e32 v68, v68
	v_exp_f32_e32 v69, v69
	v_exp_f32_e32 v70, v70
	v_exp_f32_e32 v71, v71
	v_exp_f32_e32 v72, v72
	v_exp_f32_e32 v73, v73
	v_exp_f32_e32 v74, v74
	v_exp_f32_e32 v75, v75
	v_exp_f32_e32 v76, v76
	v_exp_f32_e32 v77, v77
	v_exp_f32_e32 v78, v78
	v_exp_f32_e32 v79, v79
	v_exp_f32_e32 v80, v80
	v_exp_f32_e32 v81, v81
	v_pk_add_f32 v[14:15], v[66:67], v[68:69]
	v_pk_add_f32 v[14:15], v[14:15], v[70:71]
	v_pk_add_f32 v[14:15], v[14:15], v[72:73]
	v_cvt_pk_bf16_f32 v66, v66, v67
	v_cvt_pk_bf16_f32 v67, v68, v69
	v_cvt_pk_bf16_f32 v68, v70, v71
	v_cvt_pk_bf16_f32 v69, v72, v73
	ds_read_b64_tr_b16 v[70:71], v16 offset:21504
	ds_read_b64_tr_b16 v[72:73], v16 offset:22016
	v_pk_add_f32 v[14:15], v[14:15], v[74:75]
	v_pk_add_f32 v[14:15], v[14:15], v[76:77]
	v_pk_add_f32 v[14:15], v[14:15], v[78:79]
	v_pk_add_f32 v[14:15], v[14:15], v[80:81]
	v_cvt_pk_bf16_f32 v74, v74, v75
	v_cvt_pk_bf16_f32 v75, v76, v77
	v_cvt_pk_bf16_f32 v76, v78, v79
	v_cvt_pk_bf16_f32 v77, v80, v81
	ds_read_b64_tr_b16 v[78:79], v16 offset:18432
	ds_read_b64_tr_b16 v[80:81], v16 offset:18944
	s_waitcnt lgkmcnt(8)
	v_mfma_f32_32x32x16_bf16 v[34:49], v[66:69], v[108:111], v[34:49]
	ds_read_b64_tr_b16 v[108:109], v16 offset:23552
	ds_read_b64_tr_b16 v[110:111], v16 offset:24064
	v_pk_add_f32 v[50:51], v[50:51], v[12:13] neg_lo:[0,1] neg_hi:[0,1]
	v_pk_add_f32 v[52:53], v[52:53], v[12:13] neg_lo:[0,1] neg_hi:[0,1]
	v_pk_add_f32 v[54:55], v[54:55], v[12:13] neg_lo:[0,1] neg_hi:[0,1]
	v_pk_add_f32 v[56:57], v[56:57], v[12:13] neg_lo:[0,1] neg_hi:[0,1]
	s_waitcnt lgkmcnt(8)
	v_mfma_f32_32x32x16_bf16 v[18:33], v[66:69], v[112:115], v[18:33]
	ds_read_b64_tr_b16 v[112:113], v16 offset:22528
	ds_read_b64_tr_b16 v[114:115], v16 offset:23040
	v_pk_add_f32 v[58:59], v[58:59], v[12:13] neg_lo:[0,1] neg_hi:[0,1]
	v_pk_add_f32 v[60:61], v[60:61], v[12:13] neg_lo:[0,1] neg_hi:[0,1]
	v_pk_add_f32 v[62:63], v[62:63], v[12:13] neg_lo:[0,1] neg_hi:[0,1]
	v_pk_add_f32 v[64:65], v[64:65], v[12:13] neg_lo:[0,1] neg_hi:[0,1]
	v_exp_f32_e32 v50, v50
	v_exp_f32_e32 v51, v51
	v_exp_f32_e32 v52, v52
	v_exp_f32_e32 v53, v53
	v_exp_f32_e32 v54, v54
	s_waitcnt lgkmcnt(8)
	v_mfma_f32_32x32x16_bf16 v[34:49], v[74:77], v[120:123], v[34:49]
	ds_read_b64_tr_b16 v[120:121], v16 offset:19456
	ds_read_b64_tr_b16 v[122:123], v16 offset:19968
	v_exp_f32_e32 v55, v55
	v_exp_f32_e32 v56, v56
	v_exp_f32_e32 v57, v57
	v_exp_f32_e32 v58, v58
	v_exp_f32_e32 v59, v59
	v_exp_f32_e32 v60, v60
	s_waitcnt lgkmcnt(8)
	v_mfma_f32_32x32x16_bf16 v[18:33], v[74:77], v[70:73], v[18:33]
	v_exp_f32_e32 v61, v61
	v_exp_f32_e32 v62, v62
	v_exp_f32_e32 v63, v63
	v_exp_f32_e32 v64, v64
	v_exp_f32_e32 v65, v65
	v_pk_add_f32 v[14:15], v[14:15], v[50:51]
	v_pk_add_f32 v[14:15], v[14:15], v[52:53]
	v_pk_add_f32 v[14:15], v[14:15], v[54:55]
	v_pk_add_f32 v[14:15], v[14:15], v[56:57]
	v_cvt_pk_bf16_f32 v50, v50, v51
	v_cvt_pk_bf16_f32 v51, v52, v53
	v_cvt_pk_bf16_f32 v52, v54, v55
	v_cvt_pk_bf16_f32 v53, v56, v57
	v_pk_add_f32 v[14:15], v[14:15], v[58:59]
	v_pk_add_f32 v[14:15], v[14:15], v[60:61]
	s_waitcnt lgkmcnt(6)
	v_mfma_f32_32x32x16_bf16 v[34:49], v[50:53], v[78:81], v[34:49]
	v_pk_add_f32 v[14:15], v[14:15], v[62:63]
	v_pk_add_f32 v[14:15], v[14:15], v[64:65]
	v_cvt_pk_bf16_f32 v58, v58, v59
	v_cvt_pk_bf16_f32 v59, v60, v61
	v_cvt_pk_bf16_f32 v60, v62, v63
	v_cvt_pk_bf16_f32 v61, v64, v65
	v_add_f32_e32 v11, v11, v14
	v_add_f32_e32 v11, v11, v15
	v_mov_b32_e32 v106, v11
	v_mov_b32_e32 v107, v2
	s_waitcnt lgkmcnt(2)
	v_mfma_f32_32x32x16_bf16 v[18:33], v[50:53], v[112:115], v[18:33]
	s_waitcnt lgkmcnt(0)
	v_mfma_f32_32x32x16_bf16 v[34:49], v[58:61], v[120:123], v[34:49]
	v_mfma_f32_32x32x16_bf16 v[18:33], v[58:61], v[108:111], v[18:33]
	s_mov_b32 s100, s101
	s_andn2_b64 exec, exec, s[12:13]
	s_cbranch_execz .LBB0_575
.LBB0_568:
	s_and_b32 s14, s3, 0x2000
	s_add_i32 s84, s14, 0
	v_add3_u32 v2, s84, v225, v226
	s_waitcnt vmcnt(0) lgkmcnt(0)
	ds_write_b128 v2, v[98:101]
	v_add_u32_e32 v2, s84, v227
	v_add3_u32 v2, v2, v228, v229
	s_cmp_eq_u64 s[98:99], 0
	s_cselect_b64 s[78:79], -1, 0
	s_cselect_b64 vcc, 0, -1
	ds_write_b128 v2, v[102:105] offset:16384
	s_waitcnt lgkmcnt(0)
	s_barrier
	s_and_saveexec_b64 s[14:15], vcc
	s_cbranch_execz .LBB0_570
	s_ff1_i32_b64 s101, s[98:99]
	s_add_u32 s80, s98, -1
	s_addc_u32 s81, s99, -1
	s_and_b64 s[98:99], s[98:99], s[80:81]
	s_lshl_b32 s82, s101, 13
	s_add_u32 s80, s88, s82
	s_addc_u32 s81, s89, 0
	s_add_u32 s82, s90, s82
	s_addc_u32 s83, s91, 0
	v_lshlrev_b32_e32 v4, 7, v140
	v_lshl_or_b32 v4, v138, 1, v4
	global_load_dwordx4 v[98:101], v4, s[80:81]
	global_load_dwordx4 v[102:105], v4, s[82:83]
; #define LAS __attribute__((address_space(3)))
; DI int crow(int reg, int hi) { return (reg & 3) + 8 * (reg >> 2) + 4 * hi; }
; #define MFMA32(a, b, c) __builtin_amdgcn_mfma_f32_32x32x16_bf16((a), (b), (c), 0, 0, 0)
; template <bool CMP> DI void tile_compute(LAS unsigned char* lds, int buf, const bf16x8 (&q)[4], int lo, int hv, ASt& st, f32x16& imp0, f32x16& imp1, int jt, LAS float* wsf, int lane) {
;     const int r = lane & 31, hi = lane >> 5;
;     const LAS unsigned char* kb0 = lds + A_KT + buf * 8192 + hi * 1024;
;     f32x16 p0 = {}, p1 = {};
; #pragma unroll
;     for (int s = 0; s < 4; ++s) { const LAS unsigned char* kb = kb0 + ((r ^ (4 * s + 2 * hi)) * 16);
;         const bf16x8 a0 = *(const LAS bf16x8*)(kb + s * 2048), a1 = *(const LAS bf16x8*)(kb + s * 2048 + 512);
;         p0 = MFMA32(a0, q[s], p0); p1 = MFMA32(a1, q[s], p1); }
;     const bool dead = lo > hv;
;     const bool part = !dead && (lo > 0 || hv < 63);
;     const bool anyPart = __builtin_amdgcn_ballot_w64(part) != 0ull;
;     if (anyPart) {
; #pragma unroll
;         for (int rg = 0; rg < 16; ++rg) { const int k0 = crow(rg, hi), k1 = k0 + 32;
;             p0[rg] = (k0 >= lo && k0 <= hv) ? p0[rg] : NEGB; p1[rg] = (k1 >= lo && k1 <= hv) ? p1[rg] : NEGB; }
;     }
; DI void nsa_unit(const Ctx& c0, int b, int g, int i, LAS unsigned char* lds) {
;     ...
;             const bool more = rem != 0ull; int nn = 0;
;             if (more) { nn = __builtin_ctzll(rem); rem &= rem - 1ull; tr = tile_fetch(Kg, Vg, 64 * nn, tid); }
;             const bool selb = (mysel >> n) & 1ull;
;             const int lo = selb ? 0 : 64; const int hv = (n == i) ? ql : 63;
.LBB0_570:
	s_or_b64 exec, exec, s[14:15]
	v_lshrrev_b64 v[4:5], s100, v[116:117]
	v_add_u32_e32 v5, s84, v137
	v_add_u32_e32 v6, v5, v139
	s_cmp_eq_u32 s25, s100
	s_cselect_b64 s[80:81], -1, 0
	ds_read_b128 v[66:69], v6
	ds_read_b128 v[50:53], v6 offset:512
	v_add_u32_e32 v6, v5, v143
	v_and_b32_e32 v2, 1, v4
	ds_read_b128 v[12:15], v6 offset:2048
	ds_read_b128 v[108:111], v6 offset:2560
	v_add_u32_e32 v6, v5, v146
	v_add_u32_e32 v5, v5, v147
	ds_read_b128 v[112:115], v6 offset:4096
	ds_read_b128 v[120:123], v6 offset:4608
	v_cmp_eq_u64_e32 vcc, 0, v[2:3]
	v_cndmask_b32_e64 v4, 63, v125, s[80:81]
	v_cmp_ne_u32_e64 s[82:83], 63, v4
	v_cndmask_b32_e64 v2, 0, 64, vcc
	s_waitcnt lgkmcnt(5)
	v_mfma_f32_32x32x16_bf16 v[66:81], v[66:69], v[82:85], 0
	v_cmp_gt_u32_e64 s[80:81], v2, v4
	s_or_b64 s[14:15], s[82:83], vcc
	s_xor_b64 vcc, s[14:15], s[80:81]
	s_waitcnt lgkmcnt(4)
	v_mfma_f32_32x32x16_bf16 v[50:65], v[50:53], v[82:85], 0
	s_waitcnt lgkmcnt(3)
	v_mfma_f32_32x32x16_bf16 v[66:81], v[12:15], v[90:93], v[66:81]
	ds_read_b128 v[12:15], v5 offset:6144
	s_waitcnt lgkmcnt(3)
	v_mfma_f32_32x32x16_bf16 v[50:65], v[108:111], v[90:93], v[50:65]
	ds_read_b128 v[108:111], v5 offset:6656
	v_cndmask_b32_e64 v5, 0, 1, vcc
	v_cmp_ne_u32_e64 s[82:83], 0, v5
	s_cmp_eq_u64 s[82:83], 0
	s_cselect_b64 s[14:15], -1, 0
	s_waitcnt lgkmcnt(3)
	v_mfma_f32_32x32x16_bf16 v[66:81], v[112:115], v[86:89], v[66:81]
	s_waitcnt lgkmcnt(2)
	v_mfma_f32_32x32x16_bf16 v[50:65], v[120:123], v[86:89], v[50:65]
	s_waitcnt lgkmcnt(1)
	v_mfma_f32_32x32x16_bf16 v[66:81], v[12:15], v[94:97], v[66:81]
	s_waitcnt lgkmcnt(0)
	v_mfma_f32_32x32x16_bf16 v[50:65], v[108:111], v[94:97], v[50:65]
	s_cbranch_vccz .LBB0_572
	v_cmp_lt_u32_e32 vcc, v148, v2
	v_cmp_gt_u32_e64 s[82:83], v148, v4
	s_or_b64 vcc, s[82:83], vcc
	s_nop 6
	v_cndmask_b32_e32 v66, v66, v222, vcc
	v_cmp_lt_u32_e32 vcc, v149, v2
	v_cmp_gt_u32_e64 s[82:83], v149, v4
	s_or_b64 vcc, s[82:83], vcc
	v_cndmask_b32_e32 v50, v50, v222, vcc
	v_cmp_lt_u32_e32 vcc, v154, v2
	v_cmp_ge_u32_e64 s[82:83], v148, v4
	s_or_b64 vcc, s[82:83], vcc
	v_cndmask_b32_e32 v67, v67, v222, vcc
	v_cmp_lt_u32_e32 vcc, v155, v2
	v_cmp_gt_u32_e64 s[82:83], v155, v4
	s_or_b64 vcc, s[82:83], vcc
	v_cndmask_b32_e32 v51, v51, v222, vcc
	v_cmp_lt_u32_e32 vcc, v156, v2
	v_cmp_gt_u32_e64 s[82:83], v156, v4
	s_or_b64 vcc, s[82:83], vcc
	v_cndmask_b32_e32 v68, v68, v222, vcc
	v_cmp_lt_u32_e32 vcc, v157, v2
	v_cmp_gt_u32_e64 s[82:83], v157, v4
	s_or_b64 vcc, s[82:83], vcc
	v_cndmask_b32_e32 v52, v52, v222, vcc
	v_cmp_lt_u32_e32 vcc, v158, v2
	v_cmp_gt_u32_e64 s[82:83], v158, v4
	s_or_b64 vcc, s[82:83], vcc
	v_cndmask_b32_e32 v69, v69, v222, vcc
	v_cmp_lt_u32_e32 vcc, v159, v2
	v_cmp_gt_u32_e64 s[82:83], v159, v4
	s_or_b64 vcc, s[82:83], vcc
	v_cndmask_b32_e32 v53, v53, v222, vcc
	v_cmp_lt_u32_e32 vcc, v160, v2
	v_cmp_gt_u32_e64 s[82:83], v160, v4
	s_or_b64 vcc, s[82:83], vcc
	v_cndmask_b32_e32 v70, v70, v222, vcc
	v_cmp_lt_u32_e32 vcc, v161, v2
	v_cmp_gt_u32_e64 s[82:83], v161, v4
	s_or_b64 vcc, s[82:83], vcc
	v_cndmask_b32_e32 v54, v54, v222, vcc
	v_cmp_lt_u32_e32 vcc, v162, v2
	v_cmp_gt_u32_e64 s[82:83], v162, v4
	s_or_b64 vcc, s[82:83], vcc
	v_cndmask_b32_e32 v71, v71, v222, vcc
	v_cmp_lt_u32_e32 vcc, v163, v2
	v_cmp_gt_u32_e64 s[82:83], v163, v4
	s_or_b64 vcc, s[82:83], vcc
	v_cndmask_b32_e32 v55, v55, v222, vcc
	v_cmp_lt_u32_e32 vcc, v164, v2
	v_cmp_gt_u32_e64 s[82:83], v164, v4
	s_or_b64 vcc, s[82:83], vcc
	v_cndmask_b32_e32 v72, v72, v222, vcc
	v_cmp_lt_u32_e32 vcc, v165, v2
	v_cmp_gt_u32_e64 s[82:83], v165, v4
	s_or_b64 vcc, s[82:83], vcc
	v_cndmask_b32_e32 v56, v56, v222, vcc
	v_cmp_lt_u32_e32 vcc, v166, v2
	v_cmp_gt_u32_e64 s[82:83], v166, v4
	s_or_b64 vcc, s[82:83], vcc
	v_cndmask_b32_e32 v73, v73, v222, vcc
	v_cmp_lt_u32_e32 vcc, v167, v2
	v_cmp_gt_u32_e64 s[82:83], v167, v4
	s_or_b64 vcc, s[82:83], vcc
	v_cndmask_b32_e32 v57, v57, v222, vcc
	v_cmp_lt_u32_e32 vcc, v168, v2
	v_cmp_gt_u32_e64 s[82:83], v168, v4
	s_or_b64 vcc, s[82:83], vcc
	v_cndmask_b32_e32 v74, v74, v222, vcc
	v_cmp_lt_u32_e32 vcc, v169, v2
	v_cmp_gt_u32_e64 s[82:83], v169, v4
	s_or_b64 vcc, s[82:83], vcc
	v_cndmask_b32_e32 v58, v58, v222, vcc
	v_cmp_lt_u32_e32 vcc, v170, v2
	v_cmp_gt_u32_e64 s[82:83], v170, v4
	s_or_b64 vcc, s[82:83], vcc
	v_cndmask_b32_e32 v75, v75, v222, vcc
	v_cmp_lt_u32_e32 vcc, v171, v2
	v_cmp_gt_u32_e64 s[82:83], v171, v4
	s_or_b64 vcc, s[82:83], vcc
	v_cndmask_b32_e32 v59, v59, v222, vcc
	v_cmp_lt_u32_e32 vcc, v172, v2
	v_cmp_gt_u32_e64 s[82:83], v172, v4
	s_or_b64 vcc, s[82:83], vcc
	v_cndmask_b32_e32 v76, v76, v222, vcc
	v_cmp_lt_u32_e32 vcc, v173, v2
	v_cmp_gt_u32_e64 s[82:83], v173, v4
	s_or_b64 vcc, s[82:83], vcc
	v_cndmask_b32_e32 v60, v60, v222, vcc
	v_cmp_lt_u32_e32 vcc, v174, v2
	v_cmp_gt_u32_e64 s[82:83], v174, v4
	s_or_b64 vcc, s[82:83], vcc
	v_cndmask_b32_e32 v77, v77, v222, vcc
	v_cmp_lt_u32_e32 vcc, v175, v2
	v_cmp_gt_u32_e64 s[82:83], v175, v4
	s_or_b64 vcc, s[82:83], vcc
	v_cndmask_b32_e32 v61, v61, v222, vcc
	v_cmp_lt_u32_e32 vcc, v176, v2
	v_cmp_gt_u32_e64 s[82:83], v176, v4
	s_or_b64 vcc, s[82:83], vcc
	v_cndmask_b32_e32 v78, v78, v222, vcc
	v_cmp_lt_u32_e32 vcc, v177, v2
	v_cmp_gt_u32_e64 s[82:83], v177, v4
	s_or_b64 vcc, s[82:83], vcc
	v_cndmask_b32_e32 v62, v62, v222, vcc
	v_cmp_lt_u32_e32 vcc, v178, v2
	v_cmp_gt_u32_e64 s[82:83], v178, v4
	s_or_b64 vcc, s[82:83], vcc
	v_cndmask_b32_e32 v79, v79, v222, vcc
	v_cmp_lt_u32_e32 vcc, v179, v2
	v_cmp_gt_u32_e64 s[82:83], v179, v4
	s_or_b64 vcc, s[82:83], vcc
	v_cndmask_b32_e32 v63, v63, v222, vcc
	v_cmp_lt_u32_e32 vcc, v180, v2
	v_cmp_gt_u32_e64 s[82:83], v180, v4
	s_or_b64 vcc, s[82:83], vcc
	v_cndmask_b32_e32 v80, v80, v222, vcc
	v_cmp_lt_u32_e32 vcc, v181, v2
	v_cmp_gt_u32_e64 s[82:83], v181, v4
	s_or_b64 vcc, s[82:83], vcc
	v_cndmask_b32_e32 v64, v64, v222, vcc
	v_cmp_lt_u32_e32 vcc, v182, v2
	v_cmp_gt_u32_e64 s[82:83], v182, v4
	s_or_b64 vcc, s[82:83], vcc
	v_cndmask_b32_e32 v81, v81, v222, vcc
	v_cmp_lt_u32_e32 vcc, v183, v2
	v_cmp_gt_u32_e64 s[82:83], v183, v4
	s_or_b64 vcc, s[82:83], vcc
	v_cndmask_b32_e32 v65, v65, v222, vcc

; DI float bf2f(bf16 b) { return __uint_as_float(((unsigned)b) << 16); }
; DI void nsa_unit(const Ctx& c0, int b, int g, int i, LAS unsigned char* lds) {
;     ...
;     bf16x8 qr[4];
;     { const float* ct = (const float*)(c.ws + O_TAB) + (size_t)t * 32; const float* stb = ct + 4096 * 32;
; #pragma unroll
;       for (int s = 0; s < 2; ++s) {
;           const f32x4 c0 = *(const f32x4*)(ct + 16 * s + 8 * hi), c1 = *(const f32x4*)(ct + 16 * s + 8 * hi + 4);
;           const f32x4 s0 = *(const f32x4*)(stb + 16 * s + 8 * hi), s1 = *(const f32x4*)(stb + 16 * s + 8 * hi + 4);
;           float lo_[8], hi_[8], ol[8], oh[8];
; #pragma unroll
;           for (int j = 0; j < 8; ++j) { lo_[j] = bf2f((bf16)qn[s][j]); hi_[j] = bf2f((bf16)qn[s + 2][j]); }
; #pragma unroll
;           for (int j = 0; j < 8; ++j) { const float cc = j < 4 ? c0[j & 3] : c1[j & 3], ss = j < 4 ? s0[j & 3] : s1[j & 3];
;               ol[j] = lo_[j] * cc - hi_[j] * ss; oh[j] = hi_[j] * cc + lo_[j] * ss; }
;           qr[s] = pack8(ol[0], ol[1], ol[2], ol[3], ol[4], ol[5], ol[6], ol[7]); qr[s + 2] = pack8(oh[0], oh[1], oh[2], oh[3], oh[4], oh[5], oh[6], oh[7]); } }
;     ...
;     {
;         const bf16* Kg = (const bf16*)(c.ws + O_KS) + ((size_t)g * T + (size_t)b * SEQ) * 64;
;         const bf16* Vg = (const bf16*)(c.ws + O_VS) + ((size_t)g * T + (size_t)b * SEQ) * 64;
;         ASt st; st.m = NEGB; st.l = 0.f; st.o0 = f32x16{}; st.o1 = f32x16{};
;         unsigned long long rem = um;
;         int n = __builtin_ctzll(rem); rem &= rem - 1ull;
;         TileRegs tr = tile_fetch(Kg, Vg, 64 * n, tid);
;         int k = 0;
.LBB0_1178:
	v_lshlrev_b64 v[4:5], 7, v[2:3]
	v_lshl_add_u64 v[4:5], s[0:1], 0, v[4:5]
	v_lshlrev_b32_e32 v2, 2, v124
	v_lshl_add_u64 v[16:17], v[4:5], 0, v[2:3]
	s_mov_b64 s[14:15], 0x2200000
	v_add_co_u32_e32 v4, vcc, 0x2200000, v16
	v_lshl_add_u64 v[24:25], v[16:17], 0, s[14:15]
	s_mov_b64 s[14:15], 0x2280000
	v_addc_co_u32_e32 v5, vcc, 0, v17, vcc
	v_lshl_add_u64 v[14:15], v[16:17], 0, s[14:15]
	v_add_co_u32_e32 v16, vcc, 0x2280000, v16
	global_load_dwordx4 v[4:7], v[4:5], off
	s_nop 0
	global_load_dwordx4 v[8:11], v[24:25], off offset:16
	v_addc_co_u32_e32 v17, vcc, 0, v17, vcc
	global_load_dwordx4 v[16:19], v[16:17], off
	s_nop 0
	global_load_dwordx4 v[20:23], v[14:15], off offset:16
	v_and_b32_e32 v29, 0xffff0000, v108
	v_lshlrev_b32_e32 v28, 16, v108
	v_and_b32_e32 v27, 0xffff0000, v112
	v_lshlrev_b32_e32 v26, 16, v112
	v_ffbl_b32_e32 v2, v13
	s_add_u32 s14, s0, s2
	v_add_u32_e32 v2, 32, v2
	s_addc_u32 s15, s1, s3
	s_add_u32 s88, s14, 0x8400000
	s_addc_u32 s89, s15, 0
	s_add_u32 s90, s14, 0x9400000
	s_addc_u32 s91, s15, 0
	s_mov_b32 s6, 0
	s_mov_b64 s[14:15], 0
	s_waitcnt vmcnt(0) lgkmcnt(0)
	v_pk_mul_f32 v[30:31], v[16:17], v[28:29]
	s_nop 0
	v_pk_fma_f32 v[30:31], v[4:5], v[26:27], v[30:31] neg_lo:[0,0,1] neg_hi:[0,0,1]
	v_pk_mul_f32 v[16:17], v[16:17], v[26:27]
	v_and_b32_e32 v27, 0xffff0000, v109
	v_lshlrev_b32_e32 v26, 16, v109
	v_pk_fma_f32 v[4:5], v[4:5], v[28:29], v[16:17]
	v_and_b32_e32 v17, 0xffff0000, v113
	v_lshlrev_b32_e32 v16, 16, v113
	v_pk_mul_f32 v[28:29], v[18:19], v[26:27]
	v_cvt_pk_bf16_f32 v86, v4, v5
	v_pk_fma_f32 v[28:29], v[6:7], v[16:17], v[28:29] neg_lo:[0,0,1] neg_hi:[0,0,1]
	v_pk_mul_f32 v[16:17], v[18:19], v[16:17]
	v_and_b32_e32 v19, 0xffff0000, v110
	v_lshlrev_b32_e32 v18, 16, v110
	v_pk_fma_f32 v[6:7], v[6:7], v[26:27], v[16:17]
	v_and_b32_e32 v17, 0xffff0000, v114
	v_lshlrev_b32_e32 v16, 16, v114
	v_pk_mul_f32 v[26:27], v[20:21], v[18:19]
	v_cvt_pk_bf16_f32 v87, v6, v7
	v_pk_fma_f32 v[26:27], v[8:9], v[16:17], v[26:27] neg_lo:[0,0,1] neg_hi:[0,0,1]
	v_pk_mul_f32 v[16:17], v[20:21], v[16:17]
	v_cvt_pk_bf16_f32 v84, v26, v27
	v_pk_fma_f32 v[8:9], v[8:9], v[18:19], v[16:17]
	v_and_b32_e32 v19, 0xffff0000, v111
	v_lshlrev_b32_e32 v18, 16, v111
	v_and_b32_e32 v17, 0xffff0000, v115
	v_lshlrev_b32_e32 v16, 16, v115
	v_pk_mul_f32 v[20:21], v[22:23], v[18:19]
	v_cvt_pk_bf16_f32 v88, v8, v9
	v_pk_fma_f32 v[20:21], v[10:11], v[16:17], v[20:21] neg_lo:[0,0,1] neg_hi:[0,0,1]
	v_pk_mul_f32 v[16:17], v[22:23], v[16:17]
	v_cvt_pk_bf16_f32 v85, v20, v21
	v_pk_fma_f32 v[10:11], v[10:11], v[18:19], v[16:17]
	v_cvt_pk_bf16_f32 v82, v30, v31
	v_cvt_pk_bf16_f32 v89, v10, v11
	global_load_dwordx4 v[8:11], v[24:25], off offset:64
	global_load_dwordx4 v[4:7], v[24:25], off offset:80
	global_load_dwordx4 v[16:19], v[14:15], off offset:64
	global_load_dwordx4 v[20:23], v[14:15], off offset:80
	v_and_b32_e32 v25, 0xffff0000, v104
	v_lshlrev_b32_e32 v24, 16, v104
	v_and_b32_e32 v15, 0xffff0000, v100
	v_lshlrev_b32_e32 v14, 16, v100
	v_cvt_pk_bf16_f32 v83, v28, v29
	s_waitcnt vmcnt(0) lgkmcnt(0)
	v_pk_mul_f32 v[26:27], v[16:17], v[24:25]
	s_nop 0
	v_pk_fma_f32 v[26:27], v[8:9], v[14:15], v[26:27] neg_lo:[0,0,1] neg_hi:[0,0,1]
	v_pk_mul_f32 v[14:15], v[16:17], v[14:15]
	v_and_b32_e32 v17, 0xffff0000, v105
	v_lshlrev_b32_e32 v16, 16, v105
	v_pk_fma_f32 v[8:9], v[8:9], v[24:25], v[14:15]
	v_and_b32_e32 v15, 0xffff0000, v101
	v_lshlrev_b32_e32 v14, 16, v101
	v_pk_mul_f32 v[24:25], v[18:19], v[16:17]
	v_cvt_pk_bf16_f32 v90, v26, v27
	v_pk_fma_f32 v[24:25], v[10:11], v[14:15], v[24:25] neg_lo:[0,0,1] neg_hi:[0,0,1]
	v_pk_mul_f32 v[14:15], v[18:19], v[14:15]
	v_cvt_pk_bf16_f32 v91, v24, v25
	v_pk_fma_f32 v[10:11], v[10:11], v[16:17], v[14:15]
	v_and_b32_e32 v17, 0xffff0000, v106
	v_lshlrev_b32_e32 v16, 16, v106
	v_and_b32_e32 v15, 0xffff0000, v102
	v_lshlrev_b32_e32 v14, 16, v102
	v_pk_mul_f32 v[18:19], v[20:21], v[16:17]
	v_cvt_pk_bf16_f32 v94, v8, v9
	v_pk_fma_f32 v[18:19], v[4:5], v[14:15], v[18:19] neg_lo:[0,0,1] neg_hi:[0,0,1]
	v_pk_mul_f32 v[14:15], v[20:21], v[14:15]
	v_cvt_pk_bf16_f32 v92, v18, v19
	v_pk_fma_f32 v[4:5], v[4:5], v[16:17], v[14:15]
	v_and_b32_e32 v17, 0xffff0000, v107
	v_cvt_pk_bf16_f32 v96, v4, v5
	v_ffbl_b32_e32 v4, v12
	v_min_u32_e32 v52, v4, v2
	v_lshl_add_u64 v[4:5], v[12:13], 0, -1
	v_lshlrev_b32_e32 v16, 16, v107
	v_and_b32_e32 v50, v4, v12
	v_lshl_add_u32 v4, v52, 6, v140
	v_and_b32_e32 v15, 0xffff0000, v103
	v_lshlrev_b32_e32 v14, 16, v103
	v_pk_mul_f32 v[20:21], v[22:23], v[16:17]
	v_and_b32_e32 v51, v5, v13
	v_ashrrev_i32_e32 v5, 31, v4
	v_pk_fma_f32 v[20:21], v[6:7], v[14:15], v[20:21] neg_lo:[0,0,1] neg_hi:[0,0,1]
	v_pk_mul_f32 v[14:15], v[22:23], v[14:15]
	v_lshlrev_b64 v[4:5], 7, v[4:5]
	v_pk_fma_f32 v[6:7], v[6:7], v[16:17], v[14:15]
	v_lshl_or_b32 v4, v138, 1, v4
	v_cvt_pk_bf16_f32 v97, v6, v7
	v_lshl_add_u64 v[6:7], s[88:89], 0, v[4:5]
	v_lshl_add_u64 v[4:5], s[90:91], 0, v[4:5]
	global_load_dwordx4 v[98:101], v[6:7], off
	global_load_dwordx4 v[102:105], v[4:5], off
	v_mov_b32_e32 v16, v3
	v_mov_b32_e32 v17, v3
	v_cvt_pk_bf16_f32 v93, v20, v21
	v_cvt_pk_bf16_f32 v95, v10, v11
	v_mov_b32_e32 v2, v3
	v_mov_b32_e32 v4, v3
	v_mov_b32_e32 v5, v3
	v_mov_b32_e32 v6, v3
	v_mov_b32_e32 v7, v3
	v_mov_b32_e32 v8, v3
	v_mov_b32_e32 v9, v3
	v_mov_b32_e32 v10, v3
	v_mov_b32_e32 v11, v3
	v_mov_b32_e32 v12, v3
	v_mov_b32_e32 v13, v3
	v_mov_b32_e32 v14, v3
	v_mov_b32_e32 v15, v3
	v_mov_b64_e32 v[32:33], v[16:17]
	v_mov_b64_e32 v[48:49], v[16:17]
	v_mov_b32_e32 v107, 0xf149f2ca
	v_mov_b32_e32 v106, 0
	v_mov_b64_e32 v[30:31], v[14:15]
	v_mov_b64_e32 v[28:29], v[12:13]
	v_mov_b64_e32 v[26:27], v[10:11]
	v_mov_b64_e32 v[24:25], v[8:9]
	v_mov_b64_e32 v[22:23], v[6:7]
	v_mov_b64_e32 v[20:21], v[4:5]
	v_mov_b64_e32 v[18:19], v[2:3]
	v_mov_b64_e32 v[46:47], v[14:15]
	v_mov_b64_e32 v[44:45], v[12:13]
	v_mov_b64_e32 v[42:43], v[10:11]
	v_mov_b64_e32 v[40:41], v[8:9]
	v_mov_b64_e32 v[38:39], v[6:7]
	v_mov_b64_e32 v[36:37], v[4:5]
	v_mov_b64_e32 v[34:35], v[2:3]
	v_readfirstlane_b32 s98, v50
	v_readfirstlane_b32 s99, v51
	v_readfirstlane_b32 s100, v52
	s_branch .LBB0_1181

; #define LAS __attribute__((address_space(3)))
; #define LDS_WAIT() asm volatile("s_waitcnt lgkmcnt(0)" ::: "memory")
; #define MFMA32(a, b, c) __builtin_amdgcn_mfma_f32_32x32x16_bf16((a), (b), (c), 0, 0, 0)
; template <bool CMP> DI void tile_compute(LAS unsigned char* lds, int buf, const bf16x8 (&q)[4], int lo, int hv, ASt& st, f32x16& imp0, f32x16& imp1, int jt, LAS float* wsf, int lane) {
;     ...
;     const float alpha = __builtin_amdgcn_exp2f(st.m - mnew);
;     st.m = mnew;
;     float sum = 0.f;
;     const float msub = (!anyPart && dead) ? 1e30f : mnew;
; #pragma unroll
;     for (int rg = 0; rg < 16; ++rg) { p0[rg] = __builtin_amdgcn_exp2f(p0[rg] - msub); p1[rg] = __builtin_amdgcn_exp2f(p1[rg] - msub); sum += p0[rg] + p1[rg]; }
;     st.l = st.l * alpha + sum;
;     if (__builtin_amdgcn_ballot_w64(alpha != 1.f) != 0ull) {
;         if (hi == 0) wsf[r] = alpha;
;         LDS_WAIT();
; #pragma unroll
;         for (int g4 = 0; g4 < 4; ++g4) { const f32x4 f = *(const LAS f32x4*)(wsf + 8 * g4 + 4 * hi);
; #pragma unroll
;             for (int k = 0; k < 4; ++k) { st.o0[4 * g4 + k] *= f[k]; st.o1[4 * g4 + k] *= f[k]; if (CMP) { imp0[4 * g4 + k] *= f[k]; imp1[4 * g4 + k] *= f[k]; } } }
;         LDS_WAIT();
;     }
;     bf16x8 pa[4];
;     pa[0] = pack8(p0[0], p0[1], p0[2], p0[3], p0[4], p0[5], p0[6], p0[7]); pa[1] = pack8(p0[8], p0[9], p0[10], p0[11], p0[12], p0[13], p0[14], p0[15]);
;     pa[2] = pack8(p1[0], p1[1], p1[2], p1[3], p1[4], p1[5], p1[6], p1[7]); pa[3] = pack8(p1[8], p1[9], p1[10], p1[11], p1[12], p1[13], p1[14], p1[15]);
;     const LAS unsigned char* vb = lds + A_VT + buf * 8192 + (4 * hi + ((lane & 15) >> 2)) * 64 + ((lane >> 4) & 1) * 32 + (lane & 3) * 8;
; #pragma unroll
;     for (int s = 0; s < 4; ++s) {
;         const bf16x8 v0 = cat8(vtr(vb + s * 1024), vtr(vb + s * 1024 + 512));
;         const bf16x8 v1 = cat8(vtr(vb + 4096 + s * 1024), vtr(vb + 4096 + s * 1024 + 512));
;         st.o0 = MFMA32(pa[s], v0, st.o0); st.o1 = MFMA32(pa[s], v1, st.o1);
;     }
; DI void nsa_unit(const Ctx& c0, int b, int g, int i, LAS unsigned char* lds) {
;     ...
;         for (;;) {
;             tile_stage(tr, lds, k & 1, tid);
;             __syncthreads();
;             const bool more = rem != 0ull; int nn = 0;
;             if (more) { nn = __builtin_ctzll(rem); rem &= rem - 1ull; tr = tile_fetch(Kg, Vg, 64 * nn, tid); }
.LBB0_1180:
	s_and_b64 s[16:17], exec, s[80:81]
	s_or_b64 s[14:15], s[16:17], s[14:15]
	s_addk_i32 s6, 0x2000
	v_mul_f32_e32 v11, v106, v4
	v_add3_u32 v16, s28, v207, v191
	v_add3_u32 v16, v16, v187, v186
	ds_read_b64_tr_b16 v[108:109], v16 offset:16384
	ds_read_b64_tr_b16 v[110:111], v16 offset:16896
	ds_read_b64_tr_b16 v[112:113], v16 offset:20480
	ds_read_b64_tr_b16 v[114:115], v16 offset:20992
	ds_read_b64_tr_b16 v[120:121], v16 offset:17408
	ds_read_b64_tr_b16 v[122:123], v16 offset:17920
	v_cndmask_b32_e64 v12, v2, v218, s[82:83]
	v_mov_b32_e32 v13, v12
	v_pk_add_f32 v[66:67], v[66:67], v[12:13] neg_lo:[0,1] neg_hi:[0,1]
	v_pk_add_f32 v[68:69], v[68:69], v[12:13] neg_lo:[0,1] neg_hi:[0,1]
	v_pk_add_f32 v[70:71], v[70:71], v[12:13] neg_lo:[0,1] neg_hi:[0,1]
	v_pk_add_f32 v[72:73], v[72:73], v[12:13] neg_lo:[0,1] neg_hi:[0,1]
	v_pk_add_f32 v[74:75], v[74:75], v[12:13] neg_lo:[0,1] neg_hi:[0,1]
	v_pk_add_f32 v[76:77], v[76:77], v[12:13] neg_lo:[0,1] neg_hi:[0,1]
	v_pk_add_f32 v[78:79], v[78:79], v[12:13] neg_lo:[0,1] neg_hi:[0,1]
	v_pk_add_f32 v[80:81], v[80:81], v[12:13] neg_lo:[0,1] neg_hi:[0,1]
	v_exp_f32_e32 v66, v66
	v_exp_f32_e32 v67, v67
	v_exp_f32_e32 v68, v68
	v_exp_f32_e32 v69, v69
	v_exp_f32_e32 v70, v70
	v_exp_f32_e32 v71, v71
	v_exp_f32_e32 v72, v72
	v_exp_f32_e32 v73, v73
	v_exp_f32_e32 v74, v74
	v_exp_f32_e32 v75, v75
	v_exp_f32_e32 v76, v76
	v_exp_f32_e32 v77, v77
	v_exp_f32_e32 v78, v78
	v_exp_f32_e32 v79, v79
	v_exp_f32_e32 v80, v80
	v_exp_f32_e32 v81, v81
	v_pk_add_f32 v[14:15], v[66:67], v[68:69]
	v_pk_add_f32 v[14:15], v[14:15], v[70:71]
	v_pk_add_f32 v[14:15], v[14:15], v[72:73]
	v_cvt_pk_bf16_f32 v66, v66, v67
	v_cvt_pk_bf16_f32 v67, v68, v69
	v_cvt_pk_bf16_f32 v68, v70, v71
	v_cvt_pk_bf16_f32 v69, v72, v73
	ds_read_b64_tr_b16 v[70:71], v16 offset:21504
	ds_read_b64_tr_b16 v[72:73], v16 offset:22016
	v_pk_add_f32 v[14:15], v[14:15], v[74:75]
	v_pk_add_f32 v[14:15], v[14:15], v[76:77]
	v_pk_add_f32 v[14:15], v[14:15], v[78:79]
	v_pk_add_f32 v[14:15], v[14:15], v[80:81]
	v_cvt_pk_bf16_f32 v74, v74, v75
	v_cvt_pk_bf16_f32 v75, v76, v77
	v_cvt_pk_bf16_f32 v76, v78, v79
	v_cvt_pk_bf16_f32 v77, v80, v81
	ds_read_b64_tr_b16 v[78:79], v16 offset:18432
	ds_read_b64_tr_b16 v[80:81], v16 offset:18944
	s_waitcnt lgkmcnt(8)
	v_mfma_f32_32x32x16_bf16 v[34:49], v[66:69], v[108:111], v[34:49]
	ds_read_b64_tr_b16 v[108:109], v16 offset:23552
	ds_read_b64_tr_b16 v[110:111], v16 offset:24064
	v_pk_add_f32 v[50:51], v[50:51], v[12:13] neg_lo:[0,1] neg_hi:[0,1]
	v_pk_add_f32 v[52:53], v[52:53], v[12:13] neg_lo:[0,1] neg_hi:[0,1]
	v_pk_add_f32 v[54:55], v[54:55], v[12:13] neg_lo:[0,1] neg_hi:[0,1]
	v_pk_add_f32 v[56:57], v[56:57], v[12:13] neg_lo:[0,1] neg_hi:[0,1]
	s_waitcnt lgkmcnt(8)
	v_mfma_f32_32x32x16_bf16 v[18:33], v[66:69], v[112:115], v[18:33]
	ds_read_b64_tr_b16 v[112:113], v16 offset:22528
	ds_read_b64_tr_b16 v[114:115], v16 offset:23040
	v_pk_add_f32 v[58:59], v[58:59], v[12:13] neg_lo:[0,1] neg_hi:[0,1]
	v_pk_add_f32 v[60:61], v[60:61], v[12:13] neg_lo:[0,1] neg_hi:[0,1]
	v_pk_add_f32 v[62:63], v[62:63], v[12:13] neg_lo:[0,1] neg_hi:[0,1]
	v_pk_add_f32 v[64:65], v[64:65], v[12:13] neg_lo:[0,1] neg_hi:[0,1]
	v_exp_f32_e32 v50, v50
	v_exp_f32_e32 v51, v51
	v_exp_f32_e32 v52, v52
	v_exp_f32_e32 v53, v53
	v_exp_f32_e32 v54, v54
	s_waitcnt lgkmcnt(8)
	v_mfma_f32_32x32x16_bf16 v[34:49], v[74:77], v[120:123], v[34:49]
	ds_read_b64_tr_b16 v[120:121], v16 offset:19456
	ds_read_b64_tr_b16 v[122:123], v16 offset:19968
	v_exp_f32_e32 v55, v55
	v_exp_f32_e32 v56, v56
	v_exp_f32_e32 v57, v57
	v_exp_f32_e32 v58, v58
	v_exp_f32_e32 v59, v59
	v_exp_f32_e32 v60, v60
	s_waitcnt lgkmcnt(8)
	v_mfma_f32_32x32x16_bf16 v[18:33], v[74:77], v[70:73], v[18:33]
	v_exp_f32_e32 v61, v61
	v_exp_f32_e32 v62, v62
	v_exp_f32_e32 v63, v63
	v_exp_f32_e32 v64, v64
	v_exp_f32_e32 v65, v65
	v_pk_add_f32 v[14:15], v[14:15], v[50:51]
	v_pk_add_f32 v[14:15], v[14:15], v[52:53]
	v_pk_add_f32 v[14:15], v[14:15], v[54:55]
	v_pk_add_f32 v[14:15], v[14:15], v[56:57]
	v_cvt_pk_bf16_f32 v50, v50, v51
	v_cvt_pk_bf16_f32 v51, v52, v53
	v_cvt_pk_bf16_f32 v52, v54, v55
	v_cvt_pk_bf16_f32 v53, v56, v57
	v_pk_add_f32 v[14:15], v[14:15], v[58:59]
	v_pk_add_f32 v[14:15], v[14:15], v[60:61]
	s_waitcnt lgkmcnt(6)
	v_mfma_f32_32x32x16_bf16 v[34:49], v[50:53], v[78:81], v[34:49]
	v_pk_add_f32 v[14:15], v[14:15], v[62:63]
	v_pk_add_f32 v[14:15], v[14:15], v[64:65]
	v_cvt_pk_bf16_f32 v58, v58, v59
	v_cvt_pk_bf16_f32 v59, v60, v61
	v_cvt_pk_bf16_f32 v60, v62, v63
	v_cvt_pk_bf16_f32 v61, v64, v65
	v_add_f32_e32 v11, v11, v14
	v_add_f32_e32 v11, v11, v15
	v_mov_b32_e32 v106, v11
	v_mov_b32_e32 v107, v2
	s_waitcnt lgkmcnt(2)
	v_mfma_f32_32x32x16_bf16 v[18:33], v[50:53], v[112:115], v[18:33]
	s_waitcnt lgkmcnt(0)
	v_mfma_f32_32x32x16_bf16 v[34:49], v[58:61], v[120:123], v[34:49]
	v_mfma_f32_32x32x16_bf16 v[18:33], v[58:61], v[108:111], v[18:33]
	s_mov_b32 s100, s101
	s_andn2_b64 exec, exec, s[14:15]
	s_cbranch_execz .LBB0_1188
.LBB0_1181:
	s_and_b32 s16, s6, 0x2000
	s_add_i32 s28, s16, 0
	v_add3_u32 v2, s28, v220, v221
	s_waitcnt vmcnt(0) lgkmcnt(0)
	ds_write_b128 v2, v[98:101]
	v_add_u32_e32 v2, s28, v222
	v_add3_u32 v2, v2, v223, v224
	s_cmp_eq_u64 s[98:99], 0
	s_cselect_b64 s[80:81], -1, 0
	s_cselect_b64 vcc, 0, -1
	ds_write_b128 v2, v[102:105] offset:16384
	s_waitcnt lgkmcnt(0)
	s_barrier
	s_and_saveexec_b64 s[16:17], vcc
	s_cbranch_execz .LBB0_1183
	s_ff1_i32_b64 s101, s[98:99]
	s_add_u32 s82, s98, -1
	s_addc_u32 s83, s99, -1
	s_and_b64 s[98:99], s[98:99], s[82:83]
	s_lshl_b32 s86, s101, 13
	s_add_u32 s82, s88, s86
	s_addc_u32 s83, s89, 0
	s_add_u32 s86, s90, s86
	s_addc_u32 s87, s91, 0
	v_lshlrev_b32_e32 v4, 7, v140
	v_lshl_or_b32 v4, v138, 1, v4
	global_load_dwordx4 v[98:101], v4, s[82:83]
	global_load_dwordx4 v[102:105], v4, s[86:87]
; #define LAS __attribute__((address_space(3)))
; DI int crow(int reg, int hi) { return (reg & 3) + 8 * (reg >> 2) + 4 * hi; }
; #define MFMA32(a, b, c) __builtin_amdgcn_mfma_f32_32x32x16_bf16((a), (b), (c), 0, 0, 0)
; template <bool CMP> DI void tile_compute(LAS unsigned char* lds, int buf, const bf16x8 (&q)[4], int lo, int hv, ASt& st, f32x16& imp0, f32x16& imp1, int jt, LAS float* wsf, int lane) {
;     const int r = lane & 31, hi = lane >> 5;
;     const LAS unsigned char* kb0 = lds + A_KT + buf * 8192 + hi * 1024;
;     f32x16 p0 = {}, p1 = {};
; #pragma unroll
;     for (int s = 0; s < 4; ++s) { const LAS unsigned char* kb = kb0 + ((r ^ (4 * s + 2 * hi)) * 16);
;         const bf16x8 a0 = *(const LAS bf16x8*)(kb + s * 2048), a1 = *(const LAS bf16x8*)(kb + s * 2048 + 512);
;         p0 = MFMA32(a0, q[s], p0); p1 = MFMA32(a1, q[s], p1); }
;     const bool dead = lo > hv;
;     const bool part = !dead && (lo > 0 || hv < 63);
;     const bool anyPart = __builtin_amdgcn_ballot_w64(part) != 0ull;
;     if (anyPart) {
; #pragma unroll
;         for (int rg = 0; rg < 16; ++rg) { const int k0 = crow(rg, hi), k1 = k0 + 32;
;             p0[rg] = (k0 >= lo && k0 <= hv) ? p0[rg] : NEGB; p1[rg] = (k1 >= lo && k1 <= hv) ? p1[rg] : NEGB; }
;     }
; DI void nsa_unit(const Ctx& c0, int b, int g, int i, LAS unsigned char* lds) {
;     ...
;             const bool more = rem != 0ull; int nn = 0;
;             if (more) { nn = __builtin_ctzll(rem); rem &= rem - 1ull; tr = tile_fetch(Kg, Vg, 64 * nn, tid); }
;             const bool selb = (mysel >> n) & 1ull;
;             const int lo = selb ? 0 : 64; const int hv = (n == i) ? ql : 63;
.LBB0_1183:
	s_or_b64 exec, exec, s[16:17]
	v_lshrrev_b64 v[4:5], s100, v[116:117]
	v_add_u32_e32 v5, s28, v137
	v_add_u32_e32 v6, v5, v139
	s_cmp_eq_u32 s27, s100
	s_cselect_b64 s[82:83], -1, 0
	ds_read_b128 v[66:69], v6
	ds_read_b128 v[50:53], v6 offset:512
	v_add_u32_e32 v6, v5, v143
	v_and_b32_e32 v2, 1, v4
	ds_read_b128 v[12:15], v6 offset:2048
	ds_read_b128 v[108:111], v6 offset:2560
	v_add_u32_e32 v6, v5, v146
	v_add_u32_e32 v5, v5, v147
	ds_read_b128 v[112:115], v6 offset:4096
	ds_read_b128 v[120:123], v6 offset:4608
	v_cmp_eq_u64_e32 vcc, 0, v[2:3]
	v_cndmask_b32_e64 v4, 63, v125, s[82:83]
	v_cmp_ne_u32_e64 s[86:87], 63, v4
	v_cndmask_b32_e64 v2, 0, 64, vcc
	s_waitcnt lgkmcnt(5)
	v_mfma_f32_32x32x16_bf16 v[66:81], v[66:69], v[82:85], 0
	v_cmp_gt_u32_e64 s[82:83], v2, v4
	s_or_b64 s[16:17], s[86:87], vcc
	s_xor_b64 vcc, s[16:17], s[82:83]
	s_waitcnt lgkmcnt(4)
	v_mfma_f32_32x32x16_bf16 v[50:65], v[50:53], v[82:85], 0
	s_waitcnt lgkmcnt(3)
	v_mfma_f32_32x32x16_bf16 v[66:81], v[12:15], v[90:93], v[66:81]
	ds_read_b128 v[12:15], v5 offset:6144
	s_waitcnt lgkmcnt(3)
	v_mfma_f32_32x32x16_bf16 v[50:65], v[108:111], v[90:93], v[50:65]
	ds_read_b128 v[108:111], v5 offset:6656
	v_cndmask_b32_e64 v5, 0, 1, vcc
	v_cmp_ne_u32_e64 s[86:87], 0, v5
	s_cmp_eq_u64 s[86:87], 0
	s_cselect_b64 s[16:17], -1, 0
	s_waitcnt lgkmcnt(3)
	v_mfma_f32_32x32x16_bf16 v[66:81], v[112:115], v[86:89], v[66:81]
	s_waitcnt lgkmcnt(2)
	v_mfma_f32_32x32x16_bf16 v[50:65], v[120:123], v[86:89], v[50:65]
	s_waitcnt lgkmcnt(1)
	v_mfma_f32_32x32x16_bf16 v[66:81], v[12:15], v[94:97], v[66:81]
	s_waitcnt lgkmcnt(0)
	v_mfma_f32_32x32x16_bf16 v[50:65], v[108:111], v[94:97], v[50:65]
	s_cbranch_vccz .LBB0_1185
	v_cmp_lt_u32_e32 vcc, v148, v2
	v_cmp_gt_u32_e64 s[86:87], v148, v4
	s_or_b64 vcc, s[86:87], vcc
	s_nop 6
	v_cndmask_b32_e32 v66, v66, v217, vcc
	v_cmp_lt_u32_e32 vcc, v149, v2
	v_cmp_gt_u32_e64 s[86:87], v149, v4
	s_or_b64 vcc, s[86:87], vcc
	v_cndmask_b32_e32 v50, v50, v217, vcc
	v_cmp_lt_u32_e32 vcc, v155, v2
	v_cmp_ge_u32_e64 s[86:87], v148, v4
	s_or_b64 vcc, s[86:87], vcc
	v_cndmask_b32_e32 v67, v67, v217, vcc
	v_cmp_lt_u32_e32 vcc, v156, v2
	v_cmp_gt_u32_e64 s[86:87], v156, v4
	s_or_b64 vcc, s[86:87], vcc
	v_cndmask_b32_e32 v51, v51, v217, vcc
	v_cmp_lt_u32_e32 vcc, v157, v2
	v_cmp_gt_u32_e64 s[86:87], v157, v4
	s_or_b64 vcc, s[86:87], vcc
	v_cndmask_b32_e32 v68, v68, v217, vcc
	v_cmp_lt_u32_e32 vcc, v158, v2
	v_cmp_gt_u32_e64 s[86:87], v158, v4
	s_or_b64 vcc, s[86:87], vcc
	v_cndmask_b32_e32 v52, v52, v217, vcc
	v_cmp_lt_u32_e32 vcc, v159, v2
	v_cmp_gt_u32_e64 s[86:87], v159, v4
	s_or_b64 vcc, s[86:87], vcc
	v_cndmask_b32_e32 v69, v69, v217, vcc
	v_cmp_lt_u32_e32 vcc, v160, v2
	v_cmp_gt_u32_e64 s[86:87], v160, v4
	s_or_b64 vcc, s[86:87], vcc
	v_cndmask_b32_e32 v53, v53, v217, vcc
	v_cmp_lt_u32_e32 vcc, v161, v2
	v_cmp_gt_u32_e64 s[86:87], v161, v4
	s_or_b64 vcc, s[86:87], vcc
	v_cndmask_b32_e32 v70, v70, v217, vcc
	v_cmp_lt_u32_e32 vcc, v162, v2
	v_cmp_gt_u32_e64 s[86:87], v162, v4
	s_or_b64 vcc, s[86:87], vcc
	v_cndmask_b32_e32 v54, v54, v217, vcc
	v_cmp_lt_u32_e32 vcc, v163, v2
	v_cmp_gt_u32_e64 s[86:87], v163, v4
	s_or_b64 vcc, s[86:87], vcc
	v_cndmask_b32_e32 v71, v71, v217, vcc
	v_cmp_lt_u32_e32 vcc, v164, v2
	v_cmp_gt_u32_e64 s[86:87], v164, v4
	s_or_b64 vcc, s[86:87], vcc
	v_cndmask_b32_e32 v55, v55, v217, vcc
	v_cmp_lt_u32_e32 vcc, v165, v2
	v_cmp_gt_u32_e64 s[86:87], v165, v4
	s_or_b64 vcc, s[86:87], vcc
	v_cndmask_b32_e32 v72, v72, v217, vcc
	v_cmp_lt_u32_e32 vcc, v166, v2
	v_cmp_gt_u32_e64 s[86:87], v166, v4
	s_or_b64 vcc, s[86:87], vcc
	v_cndmask_b32_e32 v56, v56, v217, vcc
	v_cmp_lt_u32_e32 vcc, v167, v2
	v_cmp_gt_u32_e64 s[86:87], v167, v4
	s_or_b64 vcc, s[86:87], vcc
	v_cndmask_b32_e32 v73, v73, v217, vcc
	v_cmp_lt_u32_e32 vcc, v168, v2
	v_cmp_gt_u32_e64 s[86:87], v168, v4
	s_or_b64 vcc, s[86:87], vcc
	v_cndmask_b32_e32 v57, v57, v217, vcc
	v_cmp_lt_u32_e32 vcc, v169, v2
	v_cmp_gt_u32_e64 s[86:87], v169, v4
	s_or_b64 vcc, s[86:87], vcc
	v_cndmask_b32_e32 v74, v74, v217, vcc
	v_cmp_lt_u32_e32 vcc, v170, v2
	v_cmp_gt_u32_e64 s[86:87], v170, v4
	s_or_b64 vcc, s[86:87], vcc
	v_cndmask_b32_e32 v58, v58, v217, vcc
	v_cmp_lt_u32_e32 vcc, v171, v2
	v_cmp_gt_u32_e64 s[86:87], v171, v4
	s_or_b64 vcc, s[86:87], vcc
	v_cndmask_b32_e32 v75, v75, v217, vcc
	v_cmp_lt_u32_e32 vcc, v172, v2
	v_cmp_gt_u32_e64 s[86:87], v172, v4
	s_or_b64 vcc, s[86:87], vcc
	v_cndmask_b32_e32 v59, v59, v217, vcc
	v_cmp_lt_u32_e32 vcc, v173, v2
	v_cmp_gt_u32_e64 s[86:87], v173, v4
	s_or_b64 vcc, s[86:87], vcc
	v_cndmask_b32_e32 v76, v76, v217, vcc
	v_cmp_lt_u32_e32 vcc, v174, v2
	v_cmp_gt_u32_e64 s[86:87], v174, v4
	s_or_b64 vcc, s[86:87], vcc
	v_cndmask_b32_e32 v60, v60, v217, vcc
	v_cmp_lt_u32_e32 vcc, v175, v2
	v_cmp_gt_u32_e64 s[86:87], v175, v4
	s_or_b64 vcc, s[86:87], vcc
	v_cndmask_b32_e32 v77, v77, v217, vcc
	v_cmp_lt_u32_e32 vcc, v176, v2
	v_cmp_gt_u32_e64 s[86:87], v176, v4
	s_or_b64 vcc, s[86:87], vcc
	v_cndmask_b32_e32 v61, v61, v217, vcc
	v_cmp_lt_u32_e32 vcc, v177, v2
	v_cmp_gt_u32_e64 s[86:87], v177, v4
	s_or_b64 vcc, s[86:87], vcc
	v_cndmask_b32_e32 v78, v78, v217, vcc
	v_cmp_lt_u32_e32 vcc, v178, v2
	v_cmp_gt_u32_e64 s[86:87], v178, v4
	s_or_b64 vcc, s[86:87], vcc
	v_cndmask_b32_e32 v62, v62, v217, vcc
	v_cmp_lt_u32_e32 vcc, v179, v2
	v_cmp_gt_u32_e64 s[86:87], v179, v4
	s_or_b64 vcc, s[86:87], vcc
	v_cndmask_b32_e32 v79, v79, v217, vcc
	v_cmp_lt_u32_e32 vcc, v180, v2
	v_cmp_gt_u32_e64 s[86:87], v180, v4
	s_or_b64 vcc, s[86:87], vcc
	v_cndmask_b32_e32 v63, v63, v217, vcc
	v_cmp_lt_u32_e32 vcc, v181, v2
	v_cmp_gt_u32_e64 s[86:87], v181, v4
	s_or_b64 vcc, s[86:87], vcc
	v_cndmask_b32_e32 v80, v80, v217, vcc
	v_cmp_lt_u32_e32 vcc, v182, v2
	v_cmp_gt_u32_e64 s[86:87], v182, v4
	s_or_b64 vcc, s[86:87], vcc
	v_cndmask_b32_e32 v64, v64, v217, vcc
	v_cmp_lt_u32_e32 vcc, v183, v2
	v_cmp_gt_u32_e64 s[86:87], v183, v4
	s_or_b64 vcc, s[86:87], vcc
	v_cndmask_b32_e32 v81, v81, v217, vcc
	v_cmp_lt_u32_e32 vcc, v195, v2
	v_cmp_gt_u32_e64 s[86:87], v195, v4
	s_or_b64 vcc, s[86:87], vcc
	v_cndmask_b32_e32 v65, v65, v217, vcc
